# P5 epilogue: residual x loaded for all 8 row groups at once (32 loads in flight) instead of 8 serialized round trips
# speedup vs baseline: 1.0170x; 1.0170x over previous
.LBB0_1181:
	s_add_u32 s2, s96, 0x2400000
	s_barrier
	s_addc_u32 s3, s97, 0
	v_readfirstlane_b32 s9, v0
	s_ashr_i32 s5, s9, 6
	s_ashr_i32 s10, s9, 8
	s_and_b32 s1, s5, 3
	v_and_b32_e32 v1, 15, v0
	s_lshl_b32 s0, s4, 8
	s_lshl_b32 s11, s1, 5
	v_lshl_or_b32 v178, s10, 6, v1
	s_lshl_b32 s12, s8, 8
	s_or_b32 s0, s11, s0
	v_lshrrev_b32_e32 v130, 2, v0
	v_add_u32_e32 v168, s12, v178
	v_and_or_b32 v130, v130, 12, s0
	v_ashrrev_i32_e32 v169, 31, v168
	v_ashrrev_i32_e32 v131, 31, v130
	v_lshlrev_b64 v[132:133], 11, v[168:169]
	v_lshl_add_u64 v[134:135], s[2:3], 0, v[132:133]
	v_lshlrev_b64 v[132:133], 1, v[130:131]
	v_lshl_add_u64 v[134:135], v[134:135], 0, v[132:133]
	global_load_dwordx2 v[182:183], v[134:135], off
	global_load_dwordx2 v[184:185], v[134:135], off offset:32
	global_load_dwordx2 v[186:187], v[134:135], off offset:256
	global_load_dwordx2 v[180:181], v[134:135], off offset:288
	v_or_b32_e32 v166, 16, v168
	v_ashrrev_i32_e32 v167, 31, v166
	s_mov_b32 s0, 0x3f9837f0
	v_or_b32_e32 v162, 32, v168
	v_ashrrev_i32_e32 v163, 31, v162
	v_or_b32_e32 v164, 48, v168
	v_ashrrev_i32_e32 v165, 31, v164
	v_add_u32_e32 v170, 0x80, v168
	v_ashrrev_i32_e32 v171, 31, v170
	v_add_u32_e32 v172, 0x90, v168
	v_ashrrev_i32_e32 v173, 31, v172
	v_add_u32_e32 v174, 0xa0, v168
	v_ashrrev_i32_e32 v175, 31, v174
	v_add_u32_e32 v176, 0xb0, v168
	v_ashrrev_i32_e32 v177, 31, v176
	v_lshlrev_b64 v[142:143], 11, v[166:167]
	v_lshl_add_u64 v[142:143], s[2:3], 0, v[142:143]
	v_lshl_add_u64 v[142:143], v[142:143], 0, v[132:133]
	global_load_dwordx2 v[188:189], v[142:143], off
	global_load_dwordx2 v[190:191], v[142:143], off offset:32
	global_load_dwordx2 v[192:193], v[142:143], off offset:256
	global_load_dwordx2 v[194:195], v[142:143], off offset:288
	v_lshlrev_b64 v[142:143], 11, v[162:163]
	v_lshl_add_u64 v[142:143], s[2:3], 0, v[142:143]
	v_lshl_add_u64 v[142:143], v[142:143], 0, v[132:133]
	global_load_dwordx2 v[196:197], v[142:143], off
	global_load_dwordx2 v[198:199], v[142:143], off offset:32
	global_load_dwordx2 v[200:201], v[142:143], off offset:256
	global_load_dwordx2 v[202:203], v[142:143], off offset:288
	v_lshlrev_b64 v[142:143], 11, v[164:165]
	v_lshl_add_u64 v[142:143], s[2:3], 0, v[142:143]
	v_lshl_add_u64 v[142:143], v[142:143], 0, v[132:133]
	global_load_dwordx2 v[204:205], v[142:143], off
	global_load_dwordx2 v[206:207], v[142:143], off offset:32
	global_load_dwordx2 v[208:209], v[142:143], off offset:256
	global_load_dwordx2 v[210:211], v[142:143], off offset:288
	v_lshlrev_b64 v[142:143], 11, v[170:171]
	v_lshl_add_u64 v[142:143], s[2:3], 0, v[142:143]
	v_lshl_add_u64 v[142:143], v[142:143], 0, v[132:133]
	global_load_dwordx2 v[212:213], v[142:143], off
	global_load_dwordx2 v[214:215], v[142:143], off offset:32
	global_load_dwordx2 v[216:217], v[142:143], off offset:256
	global_load_dwordx2 v[218:219], v[142:143], off offset:288
	v_lshlrev_b64 v[142:143], 11, v[172:173]
	v_lshl_add_u64 v[142:143], s[2:3], 0, v[142:143]
	v_lshl_add_u64 v[142:143], v[142:143], 0, v[132:133]
	global_load_dwordx2 v[220:221], v[142:143], off
	global_load_dwordx2 v[222:223], v[142:143], off offset:32
	global_load_dwordx2 v[224:225], v[142:143], off offset:256
	global_load_dwordx2 v[226:227], v[142:143], off offset:288
	v_lshlrev_b64 v[142:143], 11, v[174:175]
	v_lshl_add_u64 v[142:143], s[2:3], 0, v[142:143]
	v_lshl_add_u64 v[142:143], v[142:143], 0, v[132:133]
	global_load_dwordx2 v[228:229], v[142:143], off
	global_load_dwordx2 v[230:231], v[142:143], off offset:32
	global_load_dwordx2 v[232:233], v[142:143], off offset:256
	global_load_dwordx2 v[234:235], v[142:143], off offset:288
	v_lshlrev_b64 v[142:143], 11, v[176:177]
	v_lshl_add_u64 v[142:143], s[2:3], 0, v[142:143]
	v_lshl_add_u64 v[142:143], v[142:143], 0, v[132:133]
	global_load_dwordx2 v[236:237], v[142:143], off
	global_load_dwordx2 v[238:239], v[142:143], off offset:32
	global_load_dwordx2 v[240:241], v[142:143], off offset:256
	global_load_dwordx2 v[242:243], v[142:143], off offset:288
	s_waitcnt vmcnt(28)
	v_lshlrev_b32_e32 v144, 16, v182
	v_and_b32_e32 v145, 0xffff0000, v182
	v_lshlrev_b32_e32 v182, 16, v183
	v_and_b32_e32 v183, 0xffff0000, v183
	v_lshlrev_b32_e32 v146, 16, v184
	v_and_b32_e32 v147, 0xffff0000, v184
	v_lshlrev_b32_e32 v184, 16, v185
	v_and_b32_e32 v185, 0xffff0000, v185
	v_lshlrev_b32_e32 v148, 16, v186
	v_and_b32_e32 v149, 0xffff0000, v186
	v_lshlrev_b32_e32 v186, 16, v187
	v_and_b32_e32 v187, 0xffff0000, v187
	v_lshlrev_b32_e32 v150, 16, v180
	v_and_b32_e32 v151, 0xffff0000, v180
	v_lshlrev_b32_e32 v180, 16, v181
	v_and_b32_e32 v181, 0xffff0000, v181
	v_pk_fma_f32 v[88:89], v[182:183], s[0:1], v[88:89] op_sel_hi:[1,0,1]
	v_pk_fma_f32 v[86:87], v[144:145], s[0:1], v[86:87] op_sel_hi:[1,0,1]
	v_pk_fma_f32 v[84:85], v[184:185], s[0:1], v[84:85] op_sel_hi:[1,0,1]
	v_pk_fma_f32 v[82:83], v[146:147], s[0:1], v[82:83] op_sel_hi:[1,0,1]
	v_pk_fma_f32 v[80:81], v[186:187], s[0:1], v[80:81] op_sel_hi:[1,0,1]
	v_pk_fma_f32 v[78:79], v[148:149], s[0:1], v[78:79] op_sel_hi:[1,0,1]
	v_pk_fma_f32 v[76:77], v[180:181], s[0:1], v[76:77] op_sel_hi:[1,0,1]
	v_pk_fma_f32 v[74:75], v[150:151], s[0:1], v[74:75] op_sel_hi:[1,0,1]
	s_nop 0
	s_waitcnt vmcnt(27)
	v_lshlrev_b32_e32 v144, 16, v188
	v_and_b32_e32 v145, 0xffff0000, v188
	v_lshlrev_b32_e32 v188, 16, v189
	v_and_b32_e32 v189, 0xffff0000, v189
	s_waitcnt vmcnt(26)
	v_lshlrev_b32_e32 v146, 16, v190
	v_and_b32_e32 v147, 0xffff0000, v190
	v_lshlrev_b32_e32 v190, 16, v191
	v_and_b32_e32 v191, 0xffff0000, v191
	s_waitcnt vmcnt(25)
	v_lshlrev_b32_e32 v148, 16, v192
	v_and_b32_e32 v149, 0xffff0000, v192
	v_lshlrev_b32_e32 v192, 16, v193
	v_and_b32_e32 v193, 0xffff0000, v193
	s_waitcnt vmcnt(24)
	v_lshlrev_b32_e32 v150, 16, v194
	v_and_b32_e32 v151, 0xffff0000, v194
	v_lshlrev_b32_e32 v194, 16, v195
	v_and_b32_e32 v195, 0xffff0000, v195
	v_pk_fma_f32 v[128:129], v[188:189], s[0:1], v[128:129] op_sel_hi:[1,0,1]
	v_pk_fma_f32 v[126:127], v[144:145], s[0:1], v[126:127] op_sel_hi:[1,0,1]
	v_pk_fma_f32 v[112:113], v[190:191], s[0:1], v[112:113] op_sel_hi:[1,0,1]
	v_pk_fma_f32 v[110:111], v[146:147], s[0:1], v[110:111] op_sel_hi:[1,0,1]
	v_pk_fma_f32 v[104:105], v[192:193], s[0:1], v[104:105] op_sel_hi:[1,0,1]
	v_pk_fma_f32 v[102:103], v[148:149], s[0:1], v[102:103] op_sel_hi:[1,0,1]
	v_pk_fma_f32 v[92:93], v[194:195], s[0:1], v[92:93] op_sel_hi:[1,0,1]
	v_pk_fma_f32 v[90:91], v[150:151], s[0:1], v[90:91] op_sel_hi:[1,0,1]
	s_nop 0
	s_waitcnt vmcnt(23)
	v_lshlrev_b32_e32 v144, 16, v196
	v_and_b32_e32 v145, 0xffff0000, v196
	v_lshlrev_b32_e32 v196, 16, v197
	v_and_b32_e32 v197, 0xffff0000, v197
	s_waitcnt vmcnt(22)
	v_lshlrev_b32_e32 v146, 16, v198
	v_and_b32_e32 v147, 0xffff0000, v198
	v_lshlrev_b32_e32 v198, 16, v199
	v_and_b32_e32 v199, 0xffff0000, v199
	s_waitcnt vmcnt(21)
	v_lshlrev_b32_e32 v148, 16, v200
	v_and_b32_e32 v149, 0xffff0000, v200
	v_lshlrev_b32_e32 v200, 16, v201
	v_and_b32_e32 v201, 0xffff0000, v201
	s_waitcnt vmcnt(20)
	v_lshlrev_b32_e32 v150, 16, v202
	v_and_b32_e32 v151, 0xffff0000, v202
	v_lshlrev_b32_e32 v202, 16, v203
	v_and_b32_e32 v203, 0xffff0000, v203
	v_pk_fma_f32 v[124:125], v[196:197], s[0:1], v[124:125] op_sel_hi:[1,0,1]
	v_pk_fma_f32 v[122:123], v[144:145], s[0:1], v[122:123] op_sel_hi:[1,0,1]
	v_pk_fma_f32 v[120:121], v[198:199], s[0:1], v[120:121] op_sel_hi:[1,0,1]
	v_pk_fma_f32 v[118:119], v[146:147], s[0:1], v[118:119] op_sel_hi:[1,0,1]
	v_pk_fma_f32 v[116:117], v[200:201], s[0:1], v[116:117] op_sel_hi:[1,0,1]
	v_pk_fma_f32 v[114:115], v[148:149], s[0:1], v[114:115] op_sel_hi:[1,0,1]
	v_pk_fma_f32 v[108:109], v[202:203], s[0:1], v[108:109] op_sel_hi:[1,0,1]
	v_pk_fma_f32 v[106:107], v[150:151], s[0:1], v[106:107] op_sel_hi:[1,0,1]
	s_nop 0
	s_waitcnt vmcnt(19)
	v_lshlrev_b32_e32 v144, 16, v204
	v_and_b32_e32 v145, 0xffff0000, v204
	v_lshlrev_b32_e32 v204, 16, v205
	v_and_b32_e32 v205, 0xffff0000, v205
	s_waitcnt vmcnt(18)
	v_lshlrev_b32_e32 v146, 16, v206
	v_and_b32_e32 v147, 0xffff0000, v206
	v_lshlrev_b32_e32 v206, 16, v207
	v_and_b32_e32 v207, 0xffff0000, v207
	s_waitcnt vmcnt(17)
	v_lshlrev_b32_e32 v148, 16, v208
	v_and_b32_e32 v149, 0xffff0000, v208
	v_lshlrev_b32_e32 v208, 16, v209
	v_and_b32_e32 v209, 0xffff0000, v209
	s_waitcnt vmcnt(16)
	v_lshlrev_b32_e32 v150, 16, v210
	v_and_b32_e32 v151, 0xffff0000, v210
	v_lshlrev_b32_e32 v210, 16, v211
	v_and_b32_e32 v211, 0xffff0000, v211
	v_pk_fma_f32 v[100:101], v[204:205], s[0:1], v[100:101] op_sel_hi:[1,0,1]
	v_pk_fma_f32 v[98:99], v[144:145], s[0:1], v[98:99] op_sel_hi:[1,0,1]
	v_pk_fma_f32 v[96:97], v[206:207], s[0:1], v[96:97] op_sel_hi:[1,0,1]
	v_pk_fma_f32 v[94:95], v[146:147], s[0:1], v[94:95] op_sel_hi:[1,0,1]
	v_pk_fma_f32 v[72:73], v[208:209], s[0:1], v[72:73] op_sel_hi:[1,0,1]
	v_pk_fma_f32 v[70:71], v[148:149], s[0:1], v[70:71] op_sel_hi:[1,0,1]
	v_pk_fma_f32 v[68:69], v[210:211], s[0:1], v[68:69] op_sel_hi:[1,0,1]
	v_pk_fma_f32 v[66:67], v[150:151], s[0:1], v[66:67] op_sel_hi:[1,0,1]
	s_nop 0
	s_waitcnt vmcnt(15)
	v_lshlrev_b32_e32 v144, 16, v212
	v_and_b32_e32 v145, 0xffff0000, v212
	v_lshlrev_b32_e32 v212, 16, v213
	v_and_b32_e32 v213, 0xffff0000, v213
	s_waitcnt vmcnt(14)
	v_lshlrev_b32_e32 v146, 16, v214
	v_and_b32_e32 v147, 0xffff0000, v214
	v_lshlrev_b32_e32 v214, 16, v215
	v_and_b32_e32 v215, 0xffff0000, v215
	s_waitcnt vmcnt(13)
	v_lshlrev_b32_e32 v148, 16, v216
	v_and_b32_e32 v149, 0xffff0000, v216
	v_lshlrev_b32_e32 v216, 16, v217
	v_and_b32_e32 v217, 0xffff0000, v217
	s_waitcnt vmcnt(12)
	v_lshlrev_b32_e32 v150, 16, v218
	v_and_b32_e32 v151, 0xffff0000, v218
	v_lshlrev_b32_e32 v218, 16, v219
	v_and_b32_e32 v219, 0xffff0000, v219
	v_pk_fma_f32 v[64:65], v[212:213], s[0:1], v[64:65] op_sel_hi:[1,0,1]
	v_pk_fma_f32 v[62:63], v[144:145], s[0:1], v[62:63] op_sel_hi:[1,0,1]
	v_pk_fma_f32 v[60:61], v[214:215], s[0:1], v[60:61] op_sel_hi:[1,0,1]
	v_pk_fma_f32 v[58:59], v[146:147], s[0:1], v[58:59] op_sel_hi:[1,0,1]
	v_pk_fma_f32 v[56:57], v[216:217], s[0:1], v[56:57] op_sel_hi:[1,0,1]
	v_pk_fma_f32 v[54:55], v[148:149], s[0:1], v[54:55] op_sel_hi:[1,0,1]
	v_pk_fma_f32 v[52:53], v[218:219], s[0:1], v[52:53] op_sel_hi:[1,0,1]
	v_pk_fma_f32 v[50:51], v[150:151], s[0:1], v[50:51] op_sel_hi:[1,0,1]
	s_nop 0
	s_waitcnt vmcnt(11)
	v_lshlrev_b32_e32 v144, 16, v220
	v_and_b32_e32 v145, 0xffff0000, v220
	v_lshlrev_b32_e32 v220, 16, v221
	v_and_b32_e32 v221, 0xffff0000, v221
	s_waitcnt vmcnt(10)
	v_lshlrev_b32_e32 v146, 16, v222
	v_and_b32_e32 v147, 0xffff0000, v222
	v_lshlrev_b32_e32 v222, 16, v223
	v_and_b32_e32 v223, 0xffff0000, v223
	s_waitcnt vmcnt(9)
	v_lshlrev_b32_e32 v148, 16, v224
	v_and_b32_e32 v149, 0xffff0000, v224
	v_lshlrev_b32_e32 v224, 16, v225
	v_and_b32_e32 v225, 0xffff0000, v225
	s_waitcnt vmcnt(8)
	v_lshlrev_b32_e32 v150, 16, v226
	v_and_b32_e32 v151, 0xffff0000, v226
	v_lshlrev_b32_e32 v226, 16, v227
	v_and_b32_e32 v227, 0xffff0000, v227
	v_pk_fma_f32 v[48:49], v[220:221], s[0:1], v[48:49] op_sel_hi:[1,0,1]
	v_pk_fma_f32 v[46:47], v[144:145], s[0:1], v[46:47] op_sel_hi:[1,0,1]
	v_pk_fma_f32 v[44:45], v[222:223], s[0:1], v[44:45] op_sel_hi:[1,0,1]
	v_pk_fma_f32 v[42:43], v[146:147], s[0:1], v[42:43] op_sel_hi:[1,0,1]
	v_pk_fma_f32 v[40:41], v[224:225], s[0:1], v[40:41] op_sel_hi:[1,0,1]
	v_pk_fma_f32 v[38:39], v[148:149], s[0:1], v[38:39] op_sel_hi:[1,0,1]
	v_pk_fma_f32 v[36:37], v[226:227], s[0:1], v[36:37] op_sel_hi:[1,0,1]
	v_pk_fma_f32 v[34:35], v[150:151], s[0:1], v[34:35] op_sel_hi:[1,0,1]
	s_nop 0
	s_waitcnt vmcnt(7)
	v_lshlrev_b32_e32 v132, 16, v228
	v_and_b32_e32 v133, 0xffff0000, v228
	v_lshlrev_b32_e32 v228, 16, v229
	v_and_b32_e32 v229, 0xffff0000, v229
	s_waitcnt vmcnt(6)
	v_lshlrev_b32_e32 v144, 16, v230
	v_and_b32_e32 v145, 0xffff0000, v230
	v_lshlrev_b32_e32 v230, 16, v231
	v_and_b32_e32 v231, 0xffff0000, v231
	s_waitcnt vmcnt(5)
	v_lshlrev_b32_e32 v146, 16, v232
	v_and_b32_e32 v147, 0xffff0000, v232
	v_lshlrev_b32_e32 v232, 16, v233
	v_and_b32_e32 v233, 0xffff0000, v233
	s_waitcnt vmcnt(4)
	v_lshlrev_b32_e32 v148, 16, v234
	v_and_b32_e32 v149, 0xffff0000, v234
	v_lshlrev_b32_e32 v234, 16, v235
	v_and_b32_e32 v235, 0xffff0000, v235
	v_pk_fma_f32 v[32:33], v[228:229], s[0:1], v[32:33] op_sel_hi:[1,0,1]
	v_pk_fma_f32 v[30:31], v[132:133], s[0:1], v[30:31] op_sel_hi:[1,0,1]
	v_pk_fma_f32 v[28:29], v[230:231], s[0:1], v[28:29] op_sel_hi:[1,0,1]
	v_pk_fma_f32 v[26:27], v[144:145], s[0:1], v[26:27] op_sel_hi:[1,0,1]
	v_pk_fma_f32 v[24:25], v[232:233], s[0:1], v[24:25] op_sel_hi:[1,0,1]
	v_pk_fma_f32 v[22:23], v[146:147], s[0:1], v[22:23] op_sel_hi:[1,0,1]
	v_pk_fma_f32 v[20:21], v[234:235], s[0:1], v[20:21] op_sel_hi:[1,0,1]
	v_pk_fma_f32 v[18:19], v[148:149], s[0:1], v[18:19] op_sel_hi:[1,0,1]
	v_add_f32_e32 v133, v86, v87
	v_add_f32_e32 v142, v88, v89
	v_add_f32_e32 v143, v82, v83
	v_add_f32_e32 v144, v84, v85
	v_add_f32_e32 v133, v133, v142
	v_add_f32_e32 v145, v78, v79
	v_add_f32_e32 v146, v80, v81
	v_add_f32_e32 v142, v143, v144
	v_add_f32_e32 v133, 0, v133
	v_add_f32_e32 v147, v74, v75
	v_add_f32_e32 v148, v76, v77
	v_add_f32_e32 v143, v145, v146
	v_add_f32_e32 v133, v142, v133
	v_add_f32_e32 v144, v147, v148
	v_add_f32_e32 v133, v143, v133
	v_add_f32_e32 v133, v144, v133
	v_mov_b32_e32 v142, v133
	s_nop 1
	v_permlane16_swap_b32_e32 v133, v142
	v_add_f32_e32 v133, v133, v142
	v_mov_b32_e32 v142, v133
	s_nop 1
	v_permlane32_swap_b32_e32 v133, v142
	v_add_f32_e32 v133, v133, v142
	v_fmamk_f32 v143, v133, 0xbc800000, v89
	v_fmamk_f32 v145, v133, 0xbc800000, v87
	v_fmamk_f32 v147, v133, 0xbc800000, v85
	v_fmamk_f32 v149, v133, 0xbc800000, v83
	v_fmamk_f32 v142, v133, 0xbc800000, v88
	v_fmamk_f32 v144, v133, 0xbc800000, v86
	v_fmamk_f32 v146, v133, 0xbc800000, v84
	v_fmamk_f32 v148, v133, 0xbc800000, v82
	v_fmamk_f32 v151, v133, 0xbc800000, v81
	v_fmamk_f32 v153, v133, 0xbc800000, v79
	v_mul_f32_e32 v145, v145, v145
	v_mul_f32_e32 v143, v143, v143
	v_mul_f32_e32 v149, v149, v149
	v_mul_f32_e32 v147, v147, v147
	v_fmamk_f32 v150, v133, 0xbc800000, v80
	v_fmamk_f32 v152, v133, 0xbc800000, v78
	v_fmamk_f32 v155, v133, 0xbc800000, v77
	v_fmamk_f32 v157, v133, 0xbc800000, v75
	v_mul_f32_e32 v153, v153, v153
	v_mul_f32_e32 v151, v151, v151
	v_fmac_f32_e32 v145, v144, v144
	v_fmac_f32_e32 v143, v142, v142
	v_fmac_f32_e32 v149, v148, v148
	v_fmac_f32_e32 v147, v146, v146
	v_fmamk_f32 v154, v133, 0xbc800000, v76
	v_fmamk_f32 v156, v133, 0xbc800000, v74
	v_mul_f32_e32 v157, v157, v157
	v_mul_f32_e32 v155, v155, v155
	v_fmac_f32_e32 v153, v152, v152
	v_fmac_f32_e32 v151, v150, v150
	v_add_f32_e32 v142, v145, v143
	v_add_f32_e32 v143, v149, v147
	v_fmac_f32_e32 v157, v156, v156
	v_fmac_f32_e32 v155, v154, v154
	v_add_f32_e32 v144, v153, v151
	v_add_f32_e32 v142, v142, v143
	v_add_f32_e32 v145, v157, v155
	v_add_f32_e32 v142, v144, v142
	v_add_f32_e32 v150, v145, v142
	s_lshl_b32 s1, s1, 3
	v_mov_b32_e32 v151, v150
	s_nop 1
	v_permlane16_swap_b32_e32 v150, v151
	v_and_b32_e32 v132, 63, v0
	v_cmp_gt_u32_e32 vcc, 16, v132
	s_add_i32 s2, s1, 0
	s_waitcnt vmcnt(3)
	v_lshlrev_b32_e32 v142, 16, v236
	v_and_b32_e32 v143, 0xffff0000, v236
	v_lshlrev_b32_e32 v236, 16, v237
	v_and_b32_e32 v237, 0xffff0000, v237
	s_waitcnt vmcnt(2)
	v_lshlrev_b32_e32 v144, 16, v238
	v_and_b32_e32 v145, 0xffff0000, v238
	v_lshlrev_b32_e32 v238, 16, v239
	v_and_b32_e32 v239, 0xffff0000, v239
	s_waitcnt vmcnt(1)
	v_lshlrev_b32_e32 v146, 16, v240
	v_and_b32_e32 v147, 0xffff0000, v240
	v_lshlrev_b32_e32 v240, 16, v241
	v_and_b32_e32 v241, 0xffff0000, v241
	s_waitcnt vmcnt(0)
	v_lshlrev_b32_e32 v148, 16, v242
	v_and_b32_e32 v149, 0xffff0000, v242
	v_lshlrev_b32_e32 v242, 16, v243
	v_and_b32_e32 v243, 0xffff0000, v243
	v_pk_fma_f32 v[16:17], v[236:237], s[0:1], v[16:17] op_sel_hi:[1,0,1]
	v_pk_fma_f32 v[14:15], v[142:143], s[0:1], v[14:15] op_sel_hi:[1,0,1]
	v_pk_fma_f32 v[12:13], v[238:239], s[0:1], v[12:13] op_sel_hi:[1,0,1]
	v_pk_fma_f32 v[10:11], v[144:145], s[0:1], v[10:11] op_sel_hi:[1,0,1]
	v_pk_fma_f32 v[8:9], v[240:241], s[0:1], v[8:9] op_sel_hi:[1,0,1]
	v_pk_fma_f32 v[6:7], v[146:147], s[0:1], v[6:7] op_sel_hi:[1,0,1]
	v_pk_fma_f32 v[4:5], v[242:243], s[0:1], v[4:5] op_sel_hi:[1,0,1]
	v_pk_fma_f32 v[2:3], v[148:149], s[0:1], v[2:3] op_sel_hi:[1,0,1]
	v_add_f32_e32 v134, v150, v151
	v_mov_b32_e32 v135, v134
	s_nop 1
	v_permlane32_swap_b32_e32 v134, v135
	s_and_saveexec_b64 s[0:1], vcc
	s_cbranch_execz .LBB0_1183
	s_lshl_b32 s3, s10, 11
	s_add_i32 s3, s2, s3
	v_mul_f32_e32 v136, 0x3c800000, v133
	v_lshl_add_u32 v133, v1, 5, s3
	v_add_f32_e32 v137, v134, v135
	ds_write_b64 v133, v[136:137]
